# acc chaining extended to the FFN-site bursts with rotating accumulators (dependency-preserving reorder)
# speedup vs baseline: 1.0196x; 1.0054x over previous
.LBB0_363:
	ds_read_b128 v[76:79], v231
	v_xor_b32_e32 v91, 64, v231
	ds_read_b128 v[80:83], v91
	ds_read_b128 v[84:87], v231 offset:2048
	ds_read_b128 v[88:91], v91 offset:2048
	s_add_u32 s8, s6, 0x100
	s_addc_u32 s9, s7, 0
	s_cmp_eq_u32 s65, 28
	s_cselect_b32 s39, s31, s9
	s_cselect_b32 s38, s33, s8
	s_cselect_b32 s11, s29, s64
	s_cselect_b32 s10, s62, s63
	v_lshl_add_u64 v[108:109], s[6:7], 0, v[172:173]
	s_add_i32 m0, s44, 0xc000
	ds_read_b128 v[92:95], v241
	v_xor_b32_e32 v195, 64, v241
	ds_read_b128 v[96:99], v195
	ds_read_b128 v[100:103], v241 offset:2048
	ds_read_b128 v[104:107], v195 offset:2048
	ds_read_b128 v[180:183], v241 offset:4096
	ds_read_b128 v[184:187], v195 offset:4096
	ds_read_b128 v[188:191], v241 offset:6144
	ds_read_b128 v[192:195], v195 offset:6144
	global_load_lds_dwordx4 v[108:109], off
	v_lshl_add_u64 v[108:109], s[6:7], 0, v[174:175]
	s_add_i32 m0, s44, 0xe000
	s_nop 0
	global_load_lds_dwordx4 v[108:109], off
	s_waitcnt lgkmcnt(8)
	s_barrier
	s_waitcnt lgkmcnt(0)
	s_setprio 1
	s_waitcnt lgkmcnt(0)
	v_mfma_f32_16x16x32_bf16 v[158:161], v[76:79], v[92:95], v[158:161]
	v_mfma_f32_16x16x32_bf16 v[158:161], v[80:83], v[96:99], v[158:161]
	v_mfma_f32_16x16x32_bf16 v[60:63], v[84:87], v[92:95], v[60:63]
	v_mfma_f32_16x16x32_bf16 v[60:63], v[88:91], v[96:99], v[60:63]
	v_mfma_f32_16x16x32_bf16 v[150:153], v[76:79], v[100:103], v[150:153]
	v_mfma_f32_16x16x32_bf16 v[150:153], v[80:83], v[104:107], v[150:153]
	v_mfma_f32_16x16x32_bf16 v[52:55], v[84:87], v[100:103], v[52:55]
	v_mfma_f32_16x16x32_bf16 v[52:55], v[88:91], v[104:107], v[52:55]
	v_mfma_f32_16x16x32_bf16 v[146:149], v[76:79], v[180:183], v[146:149]
	v_mfma_f32_16x16x32_bf16 v[146:149], v[80:83], v[184:187], v[146:149]
	v_mfma_f32_16x16x32_bf16 v[48:51], v[84:87], v[180:183], v[48:51]
	v_mfma_f32_16x16x32_bf16 v[48:51], v[88:91], v[184:187], v[48:51]
	v_mfma_f32_16x16x32_bf16 v[138:141], v[76:79], v[188:191], v[138:141]
	v_mfma_f32_16x16x32_bf16 v[138:141], v[80:83], v[192:195], v[138:141]
	v_mfma_f32_16x16x32_bf16 v[40:43], v[84:87], v[188:191], v[40:43]
	v_mfma_f32_16x16x32_bf16 v[40:43], v[88:91], v[192:195], v[40:43]
	s_setprio 0
	s_barrier
	s_add_i32 s6, s58, s42
	v_lshl_add_u64 v[216:217], s[10:11], 0, v[164:165]
	s_mov_b32 m0, s6
	ds_read_b128 v[196:199], v242
	v_xor_b32_e32 v211, 64, v242
	ds_read_b128 v[200:203], v211
	ds_read_b128 v[204:207], v242 offset:2048
	ds_read_b128 v[208:211], v211 offset:2048
	global_load_lds_dwordx4 v[216:217], off
	v_lshl_add_u64 v[244:245], s[10:11], 0, v[166:167]
	s_add_i32 m0, s6, 0x2000
	s_nop 0
	global_load_lds_dwordx4 v[244:245], off
	s_barrier
	s_waitcnt lgkmcnt(0)
	s_setprio 1
	s_waitcnt lgkmcnt(0)
	v_mfma_f32_16x16x32_bf16 v[154:157], v[196:199], v[92:95], v[154:157]
	v_mfma_f32_16x16x32_bf16 v[154:157], v[200:203], v[96:99], v[154:157]
	v_mfma_f32_16x16x32_bf16 v[56:59], v[204:207], v[92:95], v[56:59]
	v_mfma_f32_16x16x32_bf16 v[56:59], v[208:211], v[96:99], v[56:59]
	v_mfma_f32_16x16x32_bf16 v[44:47], v[204:207], v[100:103], v[44:47]
	v_mfma_f32_16x16x32_bf16 v[44:47], v[208:211], v[104:107], v[44:47]
	v_mfma_f32_16x16x32_bf16 v[36:39], v[204:207], v[180:183], v[36:39]
	v_mfma_f32_16x16x32_bf16 v[36:39], v[208:211], v[184:187], v[36:39]
	v_mfma_f32_16x16x32_bf16 v[32:35], v[204:207], v[188:191], v[32:35]
	v_mfma_f32_16x16x32_bf16 v[32:35], v[208:211], v[192:195], v[32:35]
	v_mfma_f32_16x16x32_bf16 v[92:95], v[196:199], v[100:103], v[142:145]
	v_mfma_f32_16x16x32_bf16 v[92:95], v[200:203], v[104:107], v[92:95]
	v_mfma_f32_16x16x32_bf16 v[96:99], v[196:199], v[180:183], v[134:137]
	v_mfma_f32_16x16x32_bf16 v[96:99], v[200:203], v[184:187], v[96:99]
	v_mfma_f32_16x16x32_bf16 v[100:103], v[196:199], v[188:191], v[130:133]
	v_mfma_f32_16x16x32_bf16 v[100:103], v[200:203], v[192:195], v[100:103]
	s_setprio 0
	s_mov_b32 m0, s44
	v_lshl_add_u64 v[246:247], s[38:39], 0, v[170:171]
	s_barrier
	ds_read_b128 v[104:107], v241 offset:16384
	v_xor_b32_e32 v195, 64, v241
	ds_read_b128 v[130:133], v195 offset:16384
	ds_read_b128 v[134:137], v241 offset:18432
	ds_read_b128 v[142:145], v195 offset:18432
	ds_read_b128 v[180:183], v241 offset:20480
	ds_read_b128 v[184:187], v195 offset:20480
	ds_read_b128 v[188:191], v241 offset:22528
	ds_read_b128 v[192:195], v195 offset:22528
	global_load_lds_dwordx4 v[246:247], off
	v_lshl_add_u64 v[248:249], s[38:39], 0, v[168:169]
	s_mov_b32 m0, s45
	s_nop 0
	global_load_lds_dwordx4 v[248:249], off
	s_barrier
	s_waitcnt lgkmcnt(0)
	s_setprio 1
	s_waitcnt lgkmcnt(0)
	v_mfma_f32_16x16x32_bf16 v[126:129], v[76:79], v[104:107], v[126:129]
	v_mfma_f32_16x16x32_bf16 v[126:129], v[80:83], v[130:133], v[126:129]
	v_mfma_f32_16x16x32_bf16 v[28:31], v[84:87], v[104:107], v[28:31]
	v_mfma_f32_16x16x32_bf16 v[28:31], v[88:91], v[130:133], v[28:31]
	v_mfma_f32_16x16x32_bf16 v[122:125], v[76:79], v[134:137], v[122:125]
	v_mfma_f32_16x16x32_bf16 v[122:125], v[80:83], v[142:145], v[122:125]
	v_mfma_f32_16x16x32_bf16 v[24:27], v[84:87], v[134:137], v[24:27]
	v_mfma_f32_16x16x32_bf16 v[24:27], v[88:91], v[142:145], v[24:27]
	v_mfma_f32_16x16x32_bf16 v[114:117], v[76:79], v[180:183], v[114:117]
	v_mfma_f32_16x16x32_bf16 v[114:117], v[80:83], v[184:187], v[114:117]
	v_mfma_f32_16x16x32_bf16 v[20:23], v[84:87], v[180:183], v[20:23]
	v_mfma_f32_16x16x32_bf16 v[20:23], v[88:91], v[184:187], v[20:23]
	v_mfma_f32_16x16x32_bf16 v[72:75], v[76:79], v[188:191], v[72:75]
	v_mfma_f32_16x16x32_bf16 v[72:75], v[80:83], v[192:195], v[72:75]
	v_mfma_f32_16x16x32_bf16 v[4:7], v[84:87], v[188:191], v[4:7]
	v_mfma_f32_16x16x32_bf16 v[4:7], v[88:91], v[192:195], v[4:7]
	s_setprio 0
	s_barrier
	s_add_u32 s6, s10, 0x1600000
	s_addc_u32 s7, s11, 0
	s_add_i32 s66, s59, s42
	v_lshl_add_u64 v[76:77], s[6:7], 0, v[164:165]
	s_mov_b32 m0, s66
	s_nop 0
	global_load_lds_dwordx4 v[76:77], off
	v_lshl_add_u64 v[76:77], s[6:7], 0, v[166:167]
	s_add_i32 m0, s66, 0x2000
	s_nop 0
	global_load_lds_dwordx4 v[76:77], off
	s_waitcnt vmcnt(6)
	s_barrier
	s_setprio 1
	v_mfma_f32_16x16x32_bf16 v[16:19], v[204:207], v[104:107], v[16:19]
	v_mfma_f32_16x16x32_bf16 v[16:19], v[208:211], v[130:133], v[16:19]
	v_mfma_f32_16x16x32_bf16 v[12:15], v[204:207], v[134:137], v[12:15]
	v_mfma_f32_16x16x32_bf16 v[12:15], v[208:211], v[142:145], v[12:15]
	v_mfma_f32_16x16x32_bf16 v[68:71], v[196:199], v[180:183], v[68:71]
	v_mfma_f32_16x16x32_bf16 v[68:71], v[200:203], v[184:187], v[68:71]
	v_mfma_f32_16x16x32_bf16 v[8:11], v[204:207], v[180:183], v[8:11]
	v_mfma_f32_16x16x32_bf16 v[8:11], v[208:211], v[184:187], v[8:11]
	v_mfma_f32_16x16x32_bf16 v[64:67], v[196:199], v[188:191], v[64:67]
	v_mfma_f32_16x16x32_bf16 v[64:67], v[200:203], v[192:195], v[64:67]
	v_mfma_f32_16x16x32_bf16 v[0:3], v[204:207], v[188:191], v[0:3]
	v_mfma_f32_16x16x32_bf16 v[0:3], v[208:211], v[192:195], v[0:3]
	v_mfma_f32_16x16x32_bf16 v[76:79], v[196:199], v[104:107], v[118:121]
	v_mfma_f32_16x16x32_bf16 v[76:79], v[200:203], v[130:133], v[76:79]
	v_mfma_f32_16x16x32_bf16 v[80:83], v[196:199], v[134:137], v[110:113]
	v_mfma_f32_16x16x32_bf16 v[80:83], v[200:203], v[142:145], v[80:83]
	s_setprio 0
	s_add_i32 s66, 0, 0x18000
	v_add_u32_e32 v108, s66, v229
	s_barrier
	ds_read_b128 v[84:87], v108
	v_xor_b32_e32 v111, 64, v108
	ds_read_b128 v[88:91], v111
	ds_read_b128 v[104:107], v108 offset:2048
	ds_read_b128 v[108:111], v111 offset:2048
	s_add_u32 s6, s38, 0x40000
	s_addc_u32 s7, s39, 0
	s_mov_b32 m0, s46
	v_lshl_add_u64 v[112:113], s[6:7], 0, v[170:171]
	ds_read_b128 v[118:121], v241 offset:32768
	v_xor_b32_e32 v199, 64, v241
	ds_read_b128 v[130:133], v199 offset:32768
	ds_read_b128 v[134:137], v241 offset:34816
	ds_read_b128 v[180:183], v199 offset:34816
	ds_read_b128 v[184:187], v241 offset:36864
	ds_read_b128 v[188:191], v199 offset:36864
	ds_read_b128 v[192:195], v241 offset:38912
	ds_read_b128 v[196:199], v199 offset:38912
	global_load_lds_dwordx4 v[112:113], off
	v_lshl_add_u64 v[112:113], s[6:7], 0, v[168:169]
	s_mov_b32 m0, s47
	s_nop 0
	global_load_lds_dwordx4 v[112:113], off
	s_waitcnt lgkmcnt(8)
	s_barrier
	s_waitcnt lgkmcnt(0)
	s_setprio 1
	s_waitcnt lgkmcnt(0)
	v_mfma_f32_16x16x32_bf16 v[142:145], v[84:87], v[118:121], v[158:161]
	v_mfma_f32_16x16x32_bf16 v[158:161], v[88:91], v[130:133], v[142:145]
	v_mfma_f32_16x16x32_bf16 v[142:145], v[84:87], v[134:137], v[150:153]
	v_mfma_f32_16x16x32_bf16 v[150:153], v[88:91], v[180:183], v[142:145]
	v_mfma_f32_16x16x32_bf16 v[60:63], v[104:107], v[118:121], v[60:63]
	v_mfma_f32_16x16x32_bf16 v[60:63], v[108:111], v[130:133], v[60:63]
	v_mfma_f32_16x16x32_bf16 v[52:55], v[104:107], v[134:137], v[52:55]
	v_mfma_f32_16x16x32_bf16 v[52:55], v[108:111], v[180:183], v[52:55]
	v_mfma_f32_16x16x32_bf16 v[142:145], v[84:87], v[184:187], v[146:149]
	v_mfma_f32_16x16x32_bf16 v[146:149], v[88:91], v[188:191], v[142:145]
	v_mfma_f32_16x16x32_bf16 v[48:51], v[104:107], v[184:187], v[48:51]
	v_mfma_f32_16x16x32_bf16 v[48:51], v[108:111], v[188:191], v[48:51]
	v_mfma_f32_16x16x32_bf16 v[138:141], v[84:87], v[192:195], v[138:141]
	v_mfma_f32_16x16x32_bf16 v[138:141], v[88:91], v[196:199], v[138:141]
	v_mfma_f32_16x16x32_bf16 v[40:43], v[104:107], v[192:195], v[40:43]
	v_mfma_f32_16x16x32_bf16 v[40:43], v[108:111], v[196:199], v[40:43]
	s_setprio 0
	s_barrier
	s_add_i32 s38, 0, 0x1c000
	v_add_u32_e32 v112, s38, v229
	s_add_i32 s6, s66, s42
	ds_read_b128 v[200:203], v112
	v_xor_b32_e32 v215, 64, v112
	ds_read_b128 v[204:207], v215
	ds_read_b128 v[208:211], v112 offset:2048
	ds_read_b128 v[212:215], v215 offset:2048
	v_lshl_add_u64 v[112:113], v[216:217], 0, s[14:15]
	s_mov_b32 m0, s6
	s_nop 0
	global_load_lds_dwordx4 v[112:113], off
	v_lshl_add_u64 v[112:113], v[244:245], 0, s[14:15]
	s_add_i32 m0, s6, 0x2000
	s_nop 0
	global_load_lds_dwordx4 v[112:113], off
	s_barrier
	s_waitcnt lgkmcnt(0)
	s_setprio 1
	s_waitcnt lgkmcnt(0)
	v_mfma_f32_16x16x32_bf16 v[142:145], v[200:203], v[118:121], v[154:157]
	v_mfma_f32_16x16x32_bf16 v[154:157], v[204:207], v[130:133], v[142:145]
	v_mfma_f32_16x16x32_bf16 v[92:95], v[200:203], v[134:137], v[92:95]
	v_mfma_f32_16x16x32_bf16 v[142:145], v[204:207], v[180:183], v[92:95]
	v_mfma_f32_16x16x32_bf16 v[56:59], v[208:211], v[118:121], v[56:59]
	v_mfma_f32_16x16x32_bf16 v[56:59], v[212:215], v[130:133], v[56:59]
	v_mfma_f32_16x16x32_bf16 v[44:47], v[208:211], v[134:137], v[44:47]
	v_mfma_f32_16x16x32_bf16 v[44:47], v[212:215], v[180:183], v[44:47]
	v_mfma_f32_16x16x32_bf16 v[92:95], v[200:203], v[184:187], v[96:99]
	v_mfma_f32_16x16x32_bf16 v[134:137], v[204:207], v[188:191], v[92:95]
	v_mfma_f32_16x16x32_bf16 v[36:39], v[208:211], v[184:187], v[36:39]
	v_mfma_f32_16x16x32_bf16 v[36:39], v[212:215], v[188:191], v[36:39]
	v_mfma_f32_16x16x32_bf16 v[92:95], v[200:203], v[192:195], v[100:103]
	v_mfma_f32_16x16x32_bf16 v[130:133], v[204:207], v[196:199], v[92:95]
	v_mfma_f32_16x16x32_bf16 v[32:35], v[208:211], v[192:195], v[32:35]
	v_mfma_f32_16x16x32_bf16 v[32:35], v[212:215], v[196:199], v[32:35]
	s_setprio 0
	s_mov_b32 m0, s52
	v_lshl_add_u64 v[112:113], v[246:247], 0, s[14:15]
	s_barrier
	ds_read_b128 v[92:95], v241 offset:49152
	v_xor_b32_e32 v199, 64, v241
	ds_read_b128 v[96:99], v199 offset:49152
	ds_read_b128 v[100:103], v241 offset:51200
	ds_read_b128 v[180:183], v199 offset:51200
	ds_read_b128 v[184:187], v241 offset:53248
	ds_read_b128 v[188:191], v199 offset:53248
	ds_read_b128 v[192:195], v241 offset:55296
	ds_read_b128 v[196:199], v199 offset:55296
	global_load_lds_dwordx4 v[112:113], off
	v_lshl_add_u64 v[112:113], v[248:249], 0, s[14:15]
	s_mov_b32 m0, s53
	s_nop 0
	global_load_lds_dwordx4 v[112:113], off
	s_barrier
	s_waitcnt lgkmcnt(0)
	s_setprio 1
	s_waitcnt lgkmcnt(0)
	v_mfma_f32_16x16x32_bf16 v[118:121], v[84:87], v[92:95], v[126:129]
	v_mfma_f32_16x16x32_bf16 v[126:129], v[88:91], v[96:99], v[118:121]
	v_mfma_f32_16x16x32_bf16 v[28:31], v[104:107], v[92:95], v[28:31]
	v_mfma_f32_16x16x32_bf16 v[28:31], v[108:111], v[96:99], v[28:31]
	v_mfma_f32_16x16x32_bf16 v[118:121], v[84:87], v[100:103], v[122:125]
	v_mfma_f32_16x16x32_bf16 v[122:125], v[88:91], v[180:183], v[118:121]
	v_mfma_f32_16x16x32_bf16 v[24:27], v[104:107], v[100:103], v[24:27]
	v_mfma_f32_16x16x32_bf16 v[24:27], v[108:111], v[180:183], v[24:27]
	v_mfma_f32_16x16x32_bf16 v[112:115], v[84:87], v[184:187], v[114:117]
	v_mfma_f32_16x16x32_bf16 v[114:117], v[88:91], v[188:191], v[112:115]
	v_mfma_f32_16x16x32_bf16 v[20:23], v[104:107], v[184:187], v[20:23]
	v_mfma_f32_16x16x32_bf16 v[20:23], v[108:111], v[188:191], v[20:23]
	v_mfma_f32_16x16x32_bf16 v[72:75], v[84:87], v[192:195], v[72:75]
	v_mfma_f32_16x16x32_bf16 v[72:75], v[88:91], v[196:199], v[72:75]
	v_mfma_f32_16x16x32_bf16 v[4:7], v[104:107], v[192:195], v[4:7]
	v_mfma_f32_16x16x32_bf16 v[4:7], v[108:111], v[196:199], v[4:7]
	s_setprio 0
	s_barrier
	s_add_u32 s6, s10, 0x1600080
	s_addc_u32 s7, s11, 0
	s_add_i32 s10, s38, s42
	v_lshl_add_u64 v[84:85], s[6:7], 0, v[164:165]
	s_mov_b32 m0, s10
	s_nop 0
	global_load_lds_dwordx4 v[84:85], off
	v_lshl_add_u64 v[84:85], s[6:7], 0, v[166:167]
	s_add_i32 m0, s10, 0x2000
	s_nop 0
	global_load_lds_dwordx4 v[84:85], off
	s_waitcnt vmcnt(6)
	s_barrier
	s_setprio 1
	v_mfma_f32_16x16x32_bf16 v[76:79], v[200:203], v[92:95], v[76:79]
	v_mfma_f32_16x16x32_bf16 v[118:121], v[204:207], v[96:99], v[76:79]
	v_mfma_f32_16x16x32_bf16 v[16:19], v[208:211], v[92:95], v[16:19]
	v_mfma_f32_16x16x32_bf16 v[16:19], v[212:215], v[96:99], v[16:19]
	v_mfma_f32_16x16x32_bf16 v[76:79], v[200:203], v[100:103], v[80:83]
	v_mfma_f32_16x16x32_bf16 v[110:113], v[204:207], v[180:183], v[76:79]
	v_mfma_f32_16x16x32_bf16 v[12:15], v[208:211], v[100:103], v[12:15]
	v_mfma_f32_16x16x32_bf16 v[12:15], v[212:215], v[180:183], v[12:15]
	v_mfma_f32_16x16x32_bf16 v[68:71], v[200:203], v[184:187], v[68:71]
	v_mfma_f32_16x16x32_bf16 v[68:71], v[204:207], v[188:191], v[68:71]
	v_mfma_f32_16x16x32_bf16 v[8:11], v[208:211], v[184:187], v[8:11]
	v_mfma_f32_16x16x32_bf16 v[8:11], v[212:215], v[188:191], v[8:11]
	v_mfma_f32_16x16x32_bf16 v[64:67], v[200:203], v[192:195], v[64:67]
	v_mfma_f32_16x16x32_bf16 v[64:67], v[204:207], v[196:199], v[64:67]
	v_mfma_f32_16x16x32_bf16 v[0:3], v[208:211], v[192:195], v[0:3]
	v_mfma_f32_16x16x32_bf16 v[0:3], v[212:215], v[196:199], v[0:3]
	s_setprio 0
	s_add_i32 s65, s65, 2
	s_add_u32 s63, s63, 0x100
	s_addc_u32 s64, s64, 0
	s_cmp_gt_u32 s65, 29
	s_mov_b64 s[6:7], s[8:9]
	s_barrier
	s_cbranch_scc0 .LBB0_363
	s_lshl_b32 s6, s0, 8
	s_lshl_b32 s1, s1, 7
	v_mov_b32_e32 v185, v163
	v_mov_b32_e32 v80, v225
	s_add_i32 s6, s6, s56
	s_or_b32 s1, s1, s49
	s_lshl_b32 s0, s0, 3
	v_add_u32_e32 v182, s6, v185
	v_lshl_add_u32 v180, v80, 3, s1
	v_ashrrev_i32_e32 v183, 31, v182
	v_ashrrev_i32_e32 v181, 31, v180
	v_lshl_add_u64 v[78:79], v[182:183], 2, s[12:13]
	v_lshlrev_b64 v[90:91], 2, v[180:181]
	global_load_dword v188, v[78:79], off
	global_load_dword v184, v[78:79], off offset:64
	global_load_dword v186, v[78:79], off offset:128
	global_load_dword v196, v[78:79], off offset:192
	global_load_dword v195, v[78:79], off offset:256
	global_load_dword v77, v[78:79], off offset:320
	global_load_dword v76, v[78:79], off offset:384
	global_load_dword v183, v[78:79], off offset:448
	v_lshl_add_u64 v[190:191], s[82:83], 0, v[90:91]
	v_lshl_add_u64 v[78:79], s[16:17], 0, v[90:91]
	v_lshl_add_u64 v[80:81], s[18:19], 0, v[90:91]
	global_load_dwordx4 v[94:97], v[190:191], off
	global_load_dwordx4 v[102:105], v[78:79], off
	global_load_dwordx4 v[98:101], v[80:81], off
	v_lshl_add_u64 v[192:193], s[84:85], 0, v[90:91]
	v_lshl_add_u64 v[78:79], s[20:21], 0, v[90:91]
	v_lshl_add_u64 v[80:81], s[22:23], 0, v[90:91]
	v_lshl_add_u64 v[82:83], s[24:25], 0, v[90:91]
	v_lshl_add_u64 v[90:91], s[26:27], 0, v[90:91]
	global_load_dwordx4 v[106:109], v[192:193], off
	global_load_dwordx4 v[86:89], v[78:79], off
	s_nop 0
	global_load_dwordx4 v[78:81], v[80:81], off
	s_add_i32 s0, s0, s57
	global_load_dwordx4 v[82:85], v[82:83], off
	v_add_u32_e32 v187, s0, v185
	global_load_dwordx4 v[90:93], v[90:91], off
	v_cmp_gt_i32_e64 s[10:11], 2, v185
	s_waitcnt vmcnt(0)
	v_fmamk_f32 v188, v188, 0x3a000000, v243
	v_rsq_f32_e32 v194, v188
	v_mad_i64_i32 v[188:189], s[0:1], v187, s60, 0
	v_lshl_add_u64 v[188:189], s[70:71], 0, v[188:189]
	v_pk_mul_f32 v[160:161], v[160:161], v[194:195] op_sel_hi:[1,0]
	v_pk_mul_f32 v[158:159], v[158:159], v[194:195] op_sel_hi:[1,0]
	v_pk_mul_f32 v[156:157], v[156:157], v[194:195] op_sel_hi:[1,0]
	v_pk_mul_f32 v[154:155], v[154:155], v[194:195] op_sel_hi:[1,0]
	v_lshl_add_u64 v[188:189], v[180:181], 2, v[188:189]
	s_and_saveexec_b64 s[0:1], s[10:11]
	s_cbranch_execz .LBB0_366
	v_add_co_u32_e32 v198, vcc, 0x5000, v188
	global_store_dwordx4 v[188:189], v[158:161], off
	s_nop 0
	v_addc_co_u32_e32 v199, vcc, 0, v189, vcc
	global_store_dwordx4 v[198:199], v[154:157], off offset:2048

.LBB0_840:
	ds_read_b128 v[76:79], v171
	v_xor_b32_e32 v91, 64, v171
	ds_read_b128 v[80:83], v91
	ds_read_b128 v[84:87], v171 offset:2048
	ds_read_b128 v[88:91], v91 offset:2048
	s_add_u32 s10, s8, 0x100
	s_addc_u32 s11, s9, 0
	s_cmp_eq_u32 s67, 28
	s_cselect_b32 s43, s33, s11
	s_cselect_b32 s42, s37, s10
	s_cselect_b32 s13, s35, s66
	s_cselect_b32 s12, s64, s65
	v_lshl_add_u64 v[108:109], s[8:9], 0, v[180:181]
	s_add_i32 m0, s48, 0xc000
	ds_read_b128 v[92:95], v173
	v_xor_b32_e32 v203, 64, v173
	ds_read_b128 v[96:99], v203
	ds_read_b128 v[100:103], v173 offset:2048
	ds_read_b128 v[104:107], v203 offset:2048
	ds_read_b128 v[188:191], v173 offset:4096
	ds_read_b128 v[192:195], v203 offset:4096
	ds_read_b128 v[196:199], v173 offset:6144
	ds_read_b128 v[200:203], v203 offset:6144
	global_load_lds_dwordx4 v[108:109], off
	v_lshl_add_u64 v[108:109], s[8:9], 0, v[182:183]
	s_add_i32 m0, s48, 0xe000
	s_nop 0
	global_load_lds_dwordx4 v[108:109], off
	s_waitcnt lgkmcnt(8)
	s_barrier
	s_waitcnt lgkmcnt(0)
	s_setprio 1
	s_waitcnt lgkmcnt(0)
	v_mfma_f32_16x16x32_bf16 v[158:161], v[76:79], v[92:95], v[158:161]
	v_mfma_f32_16x16x32_bf16 v[158:161], v[80:83], v[96:99], v[158:161]
	v_mfma_f32_16x16x32_bf16 v[60:63], v[84:87], v[92:95], v[60:63]
	v_mfma_f32_16x16x32_bf16 v[60:63], v[88:91], v[96:99], v[60:63]
	v_mfma_f32_16x16x32_bf16 v[150:153], v[76:79], v[100:103], v[150:153]
	v_mfma_f32_16x16x32_bf16 v[150:153], v[80:83], v[104:107], v[150:153]
	v_mfma_f32_16x16x32_bf16 v[52:55], v[84:87], v[100:103], v[52:55]
	v_mfma_f32_16x16x32_bf16 v[52:55], v[88:91], v[104:107], v[52:55]
	v_mfma_f32_16x16x32_bf16 v[146:149], v[76:79], v[188:191], v[146:149]
	v_mfma_f32_16x16x32_bf16 v[146:149], v[80:83], v[192:195], v[146:149]
	v_mfma_f32_16x16x32_bf16 v[48:51], v[84:87], v[188:191], v[48:51]
	v_mfma_f32_16x16x32_bf16 v[48:51], v[88:91], v[192:195], v[48:51]
	v_mfma_f32_16x16x32_bf16 v[138:141], v[76:79], v[196:199], v[138:141]
	v_mfma_f32_16x16x32_bf16 v[138:141], v[80:83], v[200:203], v[138:141]
	v_mfma_f32_16x16x32_bf16 v[40:43], v[84:87], v[196:199], v[40:43]
	v_mfma_f32_16x16x32_bf16 v[40:43], v[88:91], v[200:203], v[40:43]
	s_setprio 0
	s_barrier
	s_add_i32 s8, s60, s46
	v_lshl_add_u64 v[220:221], s[12:13], 0, v[164:165]
	s_mov_b32 m0, s8
	ds_read_b128 v[204:207], v175
	v_xor_b32_e32 v219, 64, v175
	ds_read_b128 v[208:211], v219
	ds_read_b128 v[212:215], v175 offset:2048
	ds_read_b128 v[216:219], v219 offset:2048
	global_load_lds_dwordx4 v[220:221], off
	v_lshl_add_u64 v[238:239], s[12:13], 0, v[166:167]
	s_add_i32 m0, s8, 0x2000
	s_nop 0
	global_load_lds_dwordx4 v[238:239], off
	s_barrier
	s_waitcnt lgkmcnt(0)
	s_setprio 1
	s_waitcnt lgkmcnt(0)
	v_mfma_f32_16x16x32_bf16 v[154:157], v[204:207], v[92:95], v[154:157]
	v_mfma_f32_16x16x32_bf16 v[154:157], v[208:211], v[96:99], v[154:157]
	v_mfma_f32_16x16x32_bf16 v[56:59], v[212:215], v[92:95], v[56:59]
	v_mfma_f32_16x16x32_bf16 v[56:59], v[216:219], v[96:99], v[56:59]
	v_mfma_f32_16x16x32_bf16 v[44:47], v[212:215], v[100:103], v[44:47]
	v_mfma_f32_16x16x32_bf16 v[44:47], v[216:219], v[104:107], v[44:47]
	v_mfma_f32_16x16x32_bf16 v[36:39], v[212:215], v[188:191], v[36:39]
	v_mfma_f32_16x16x32_bf16 v[36:39], v[216:219], v[192:195], v[36:39]
	v_mfma_f32_16x16x32_bf16 v[32:35], v[212:215], v[196:199], v[32:35]
	v_mfma_f32_16x16x32_bf16 v[32:35], v[216:219], v[200:203], v[32:35]
	v_mfma_f32_16x16x32_bf16 v[92:95], v[204:207], v[100:103], v[142:145]
	v_mfma_f32_16x16x32_bf16 v[92:95], v[208:211], v[104:107], v[92:95]
	v_mfma_f32_16x16x32_bf16 v[96:99], v[204:207], v[188:191], v[134:137]
	v_mfma_f32_16x16x32_bf16 v[96:99], v[208:211], v[192:195], v[96:99]
	v_mfma_f32_16x16x32_bf16 v[100:103], v[204:207], v[196:199], v[130:133]
	v_mfma_f32_16x16x32_bf16 v[100:103], v[208:211], v[200:203], v[100:103]
	s_setprio 0
	s_mov_b32 m0, s48
	v_lshl_add_u64 v[240:241], s[42:43], 0, v[178:179]
	s_barrier
	ds_read_b128 v[104:107], v173 offset:16384
	v_xor_b32_e32 v203, 64, v173
	ds_read_b128 v[130:133], v203 offset:16384
	ds_read_b128 v[134:137], v173 offset:18432
	ds_read_b128 v[142:145], v203 offset:18432
	ds_read_b128 v[188:191], v173 offset:20480
	ds_read_b128 v[192:195], v203 offset:20480
	ds_read_b128 v[196:199], v173 offset:22528
	ds_read_b128 v[200:203], v203 offset:22528
	global_load_lds_dwordx4 v[240:241], off
	v_lshl_add_u64 v[242:243], s[42:43], 0, v[176:177]
	s_mov_b32 m0, s49
	s_nop 0
	global_load_lds_dwordx4 v[242:243], off
	s_barrier
	s_waitcnt lgkmcnt(0)
	s_setprio 1
	s_waitcnt lgkmcnt(0)
	v_mfma_f32_16x16x32_bf16 v[126:129], v[76:79], v[104:107], v[126:129]
	v_mfma_f32_16x16x32_bf16 v[126:129], v[80:83], v[130:133], v[126:129]
	v_mfma_f32_16x16x32_bf16 v[28:31], v[84:87], v[104:107], v[28:31]
	v_mfma_f32_16x16x32_bf16 v[28:31], v[88:91], v[130:133], v[28:31]
	v_mfma_f32_16x16x32_bf16 v[122:125], v[76:79], v[134:137], v[122:125]
	v_mfma_f32_16x16x32_bf16 v[122:125], v[80:83], v[142:145], v[122:125]
	v_mfma_f32_16x16x32_bf16 v[24:27], v[84:87], v[134:137], v[24:27]
	v_mfma_f32_16x16x32_bf16 v[24:27], v[88:91], v[142:145], v[24:27]
	v_mfma_f32_16x16x32_bf16 v[114:117], v[76:79], v[188:191], v[114:117]
	v_mfma_f32_16x16x32_bf16 v[114:117], v[80:83], v[192:195], v[114:117]
	v_mfma_f32_16x16x32_bf16 v[20:23], v[84:87], v[188:191], v[20:23]
	v_mfma_f32_16x16x32_bf16 v[20:23], v[88:91], v[192:195], v[20:23]
	v_mfma_f32_16x16x32_bf16 v[72:75], v[76:79], v[196:199], v[72:75]
	v_mfma_f32_16x16x32_bf16 v[72:75], v[80:83], v[200:203], v[72:75]
	v_mfma_f32_16x16x32_bf16 v[4:7], v[84:87], v[196:199], v[4:7]
	v_mfma_f32_16x16x32_bf16 v[4:7], v[88:91], v[200:203], v[4:7]
	s_setprio 0
	s_barrier
	s_add_u32 s8, s12, 0x1600000
	s_addc_u32 s9, s13, 0
	s_add_i32 s68, s61, s46
	v_lshl_add_u64 v[76:77], s[8:9], 0, v[164:165]
	s_mov_b32 m0, s68
	s_nop 0
	global_load_lds_dwordx4 v[76:77], off
	v_lshl_add_u64 v[76:77], s[8:9], 0, v[166:167]
	s_add_i32 m0, s68, 0x2000
	s_nop 0
	global_load_lds_dwordx4 v[76:77], off
	s_waitcnt vmcnt(6)
	s_barrier
	s_setprio 1
	v_mfma_f32_16x16x32_bf16 v[16:19], v[212:215], v[104:107], v[16:19]
	v_mfma_f32_16x16x32_bf16 v[16:19], v[216:219], v[130:133], v[16:19]
	v_mfma_f32_16x16x32_bf16 v[12:15], v[212:215], v[134:137], v[12:15]
	v_mfma_f32_16x16x32_bf16 v[12:15], v[216:219], v[142:145], v[12:15]
	v_mfma_f32_16x16x32_bf16 v[68:71], v[204:207], v[188:191], v[68:71]
	v_mfma_f32_16x16x32_bf16 v[68:71], v[208:211], v[192:195], v[68:71]
	v_mfma_f32_16x16x32_bf16 v[8:11], v[212:215], v[188:191], v[8:11]
	v_mfma_f32_16x16x32_bf16 v[8:11], v[216:219], v[192:195], v[8:11]
	v_mfma_f32_16x16x32_bf16 v[64:67], v[204:207], v[196:199], v[64:67]
	v_mfma_f32_16x16x32_bf16 v[64:67], v[208:211], v[200:203], v[64:67]
	v_mfma_f32_16x16x32_bf16 v[0:3], v[212:215], v[196:199], v[0:3]
	v_mfma_f32_16x16x32_bf16 v[0:3], v[216:219], v[200:203], v[0:3]
	v_mfma_f32_16x16x32_bf16 v[76:79], v[204:207], v[104:107], v[118:121]
	v_mfma_f32_16x16x32_bf16 v[76:79], v[208:211], v[130:133], v[76:79]
	v_mfma_f32_16x16x32_bf16 v[80:83], v[204:207], v[134:137], v[110:113]
	v_mfma_f32_16x16x32_bf16 v[80:83], v[208:211], v[142:145], v[80:83]
	s_setprio 0
	s_add_i32 s68, 0, 0x18000
	v_add_u32_e32 v108, s68, v169
	s_barrier
	ds_read_b128 v[84:87], v108
	v_xor_b32_e32 v111, 64, v108
	ds_read_b128 v[88:91], v111
	ds_read_b128 v[104:107], v108 offset:2048
	ds_read_b128 v[108:111], v111 offset:2048
	s_add_u32 s8, s42, 0x40000
	s_addc_u32 s9, s43, 0
	s_mov_b32 m0, s50
	v_lshl_add_u64 v[112:113], s[8:9], 0, v[178:179]
	ds_read_b128 v[118:121], v173 offset:32768
	v_xor_b32_e32 v207, 64, v173
	ds_read_b128 v[130:133], v207 offset:32768
	ds_read_b128 v[134:137], v173 offset:34816
	ds_read_b128 v[188:191], v207 offset:34816
	ds_read_b128 v[192:195], v173 offset:36864
	ds_read_b128 v[196:199], v207 offset:36864
	ds_read_b128 v[200:203], v173 offset:38912
	ds_read_b128 v[204:207], v207 offset:38912
	global_load_lds_dwordx4 v[112:113], off
	v_lshl_add_u64 v[112:113], s[8:9], 0, v[176:177]
	s_mov_b32 m0, s51
	s_nop 0
	global_load_lds_dwordx4 v[112:113], off
	s_waitcnt lgkmcnt(8)
	s_barrier
	s_waitcnt lgkmcnt(0)
	s_setprio 1
	s_waitcnt lgkmcnt(0)
	v_mfma_f32_16x16x32_bf16 v[142:145], v[84:87], v[118:121], v[158:161]
	v_mfma_f32_16x16x32_bf16 v[158:161], v[88:91], v[130:133], v[142:145]
	v_mfma_f32_16x16x32_bf16 v[142:145], v[84:87], v[134:137], v[150:153]
	v_mfma_f32_16x16x32_bf16 v[150:153], v[88:91], v[188:191], v[142:145]
	v_mfma_f32_16x16x32_bf16 v[60:63], v[104:107], v[118:121], v[60:63]
	v_mfma_f32_16x16x32_bf16 v[60:63], v[108:111], v[130:133], v[60:63]
	v_mfma_f32_16x16x32_bf16 v[52:55], v[104:107], v[134:137], v[52:55]
	v_mfma_f32_16x16x32_bf16 v[52:55], v[108:111], v[188:191], v[52:55]
	v_mfma_f32_16x16x32_bf16 v[142:145], v[84:87], v[192:195], v[146:149]
	v_mfma_f32_16x16x32_bf16 v[146:149], v[88:91], v[196:199], v[142:145]
	v_mfma_f32_16x16x32_bf16 v[48:51], v[104:107], v[192:195], v[48:51]
	v_mfma_f32_16x16x32_bf16 v[48:51], v[108:111], v[196:199], v[48:51]
	v_mfma_f32_16x16x32_bf16 v[138:141], v[84:87], v[200:203], v[138:141]
	v_mfma_f32_16x16x32_bf16 v[138:141], v[88:91], v[204:207], v[138:141]
	v_mfma_f32_16x16x32_bf16 v[40:43], v[104:107], v[200:203], v[40:43]
	v_mfma_f32_16x16x32_bf16 v[40:43], v[108:111], v[204:207], v[40:43]
	s_setprio 0
	s_barrier
	s_add_i32 s42, 0, 0x1c000
	v_add_u32_e32 v112, s42, v169
	s_add_i32 s8, s68, s46
	ds_read_b128 v[208:211], v112
	v_xor_b32_e32 v237, 64, v112
	ds_read_b128 v[212:215], v237
	ds_read_b128 v[216:219], v112 offset:2048
	ds_read_b128 v[234:237], v237 offset:2048
	v_lshl_add_u64 v[112:113], v[220:221], 0, s[18:19]
	s_mov_b32 m0, s8
	s_nop 0
	global_load_lds_dwordx4 v[112:113], off
	v_lshl_add_u64 v[112:113], v[238:239], 0, s[18:19]
	s_add_i32 m0, s8, 0x2000
	s_nop 0
	global_load_lds_dwordx4 v[112:113], off
	s_barrier
	s_waitcnt lgkmcnt(0)
	s_setprio 1
	s_waitcnt lgkmcnt(0)
	v_mfma_f32_16x16x32_bf16 v[142:145], v[208:211], v[118:121], v[154:157]
	v_mfma_f32_16x16x32_bf16 v[154:157], v[212:215], v[130:133], v[142:145]
	v_mfma_f32_16x16x32_bf16 v[92:95], v[208:211], v[134:137], v[92:95]
	v_mfma_f32_16x16x32_bf16 v[142:145], v[212:215], v[188:191], v[92:95]
	v_mfma_f32_16x16x32_bf16 v[56:59], v[216:219], v[118:121], v[56:59]
	v_mfma_f32_16x16x32_bf16 v[56:59], v[234:237], v[130:133], v[56:59]
	v_mfma_f32_16x16x32_bf16 v[44:47], v[216:219], v[134:137], v[44:47]
	v_mfma_f32_16x16x32_bf16 v[44:47], v[234:237], v[188:191], v[44:47]
	v_mfma_f32_16x16x32_bf16 v[92:95], v[208:211], v[192:195], v[96:99]
	v_mfma_f32_16x16x32_bf16 v[134:137], v[212:215], v[196:199], v[92:95]
	v_mfma_f32_16x16x32_bf16 v[36:39], v[216:219], v[192:195], v[36:39]
	v_mfma_f32_16x16x32_bf16 v[36:39], v[234:237], v[196:199], v[36:39]
	v_mfma_f32_16x16x32_bf16 v[92:95], v[208:211], v[200:203], v[100:103]
	v_mfma_f32_16x16x32_bf16 v[130:133], v[212:215], v[204:207], v[92:95]
	v_mfma_f32_16x16x32_bf16 v[32:35], v[216:219], v[200:203], v[32:35]
	v_mfma_f32_16x16x32_bf16 v[32:35], v[234:237], v[204:207], v[32:35]
	s_setprio 0
	s_mov_b32 m0, s54
	v_lshl_add_u64 v[112:113], v[240:241], 0, s[18:19]
	s_barrier
	ds_read_b128 v[92:95], v173 offset:49152
	v_xor_b32_e32 v207, 64, v173
	ds_read_b128 v[96:99], v207 offset:49152
	ds_read_b128 v[100:103], v173 offset:51200
	ds_read_b128 v[188:191], v207 offset:51200
	ds_read_b128 v[192:195], v173 offset:53248
	ds_read_b128 v[196:199], v207 offset:53248
	ds_read_b128 v[200:203], v173 offset:55296
	ds_read_b128 v[204:207], v207 offset:55296
	global_load_lds_dwordx4 v[112:113], off
	v_lshl_add_u64 v[112:113], v[242:243], 0, s[18:19]
	s_mov_b32 m0, s55
	s_nop 0
	global_load_lds_dwordx4 v[112:113], off
	s_barrier
	s_waitcnt lgkmcnt(0)
	s_setprio 1
	s_waitcnt lgkmcnt(0)
	v_mfma_f32_16x16x32_bf16 v[118:121], v[84:87], v[92:95], v[126:129]
	v_mfma_f32_16x16x32_bf16 v[126:129], v[88:91], v[96:99], v[118:121]
	v_mfma_f32_16x16x32_bf16 v[28:31], v[104:107], v[92:95], v[28:31]
	v_mfma_f32_16x16x32_bf16 v[28:31], v[108:111], v[96:99], v[28:31]
	v_mfma_f32_16x16x32_bf16 v[118:121], v[84:87], v[100:103], v[122:125]
	v_mfma_f32_16x16x32_bf16 v[122:125], v[88:91], v[188:191], v[118:121]
	v_mfma_f32_16x16x32_bf16 v[24:27], v[104:107], v[100:103], v[24:27]
	v_mfma_f32_16x16x32_bf16 v[24:27], v[108:111], v[188:191], v[24:27]
	v_mfma_f32_16x16x32_bf16 v[112:115], v[84:87], v[192:195], v[114:117]
	v_mfma_f32_16x16x32_bf16 v[114:117], v[88:91], v[196:199], v[112:115]
	v_mfma_f32_16x16x32_bf16 v[20:23], v[104:107], v[192:195], v[20:23]
	v_mfma_f32_16x16x32_bf16 v[20:23], v[108:111], v[196:199], v[20:23]
	v_mfma_f32_16x16x32_bf16 v[72:75], v[84:87], v[200:203], v[72:75]
	v_mfma_f32_16x16x32_bf16 v[72:75], v[88:91], v[204:207], v[72:75]
	v_mfma_f32_16x16x32_bf16 v[4:7], v[104:107], v[200:203], v[4:7]
	v_mfma_f32_16x16x32_bf16 v[4:7], v[108:111], v[204:207], v[4:7]
	s_setprio 0
	s_barrier
	s_add_u32 s8, s12, 0x1600080
	s_addc_u32 s9, s13, 0
	s_add_i32 s12, s42, s46
	v_lshl_add_u64 v[84:85], s[8:9], 0, v[164:165]
	s_mov_b32 m0, s12
	s_nop 0
	global_load_lds_dwordx4 v[84:85], off
	v_lshl_add_u64 v[84:85], s[8:9], 0, v[166:167]
	s_add_i32 m0, s12, 0x2000
	s_nop 0
	global_load_lds_dwordx4 v[84:85], off
	s_waitcnt vmcnt(6)
	s_barrier
	s_setprio 1
	v_mfma_f32_16x16x32_bf16 v[76:79], v[208:211], v[92:95], v[76:79]
	v_mfma_f32_16x16x32_bf16 v[118:121], v[212:215], v[96:99], v[76:79]
	v_mfma_f32_16x16x32_bf16 v[16:19], v[216:219], v[92:95], v[16:19]
	v_mfma_f32_16x16x32_bf16 v[16:19], v[234:237], v[96:99], v[16:19]
	v_mfma_f32_16x16x32_bf16 v[76:79], v[208:211], v[100:103], v[80:83]
	v_mfma_f32_16x16x32_bf16 v[110:113], v[212:215], v[188:191], v[76:79]
	v_mfma_f32_16x16x32_bf16 v[12:15], v[216:219], v[100:103], v[12:15]
	v_mfma_f32_16x16x32_bf16 v[12:15], v[234:237], v[188:191], v[12:15]
	v_mfma_f32_16x16x32_bf16 v[68:71], v[208:211], v[192:195], v[68:71]
	v_mfma_f32_16x16x32_bf16 v[68:71], v[212:215], v[196:199], v[68:71]
	v_mfma_f32_16x16x32_bf16 v[8:11], v[216:219], v[192:195], v[8:11]
	v_mfma_f32_16x16x32_bf16 v[8:11], v[234:237], v[196:199], v[8:11]
	v_mfma_f32_16x16x32_bf16 v[64:67], v[208:211], v[200:203], v[64:67]
	v_mfma_f32_16x16x32_bf16 v[64:67], v[212:215], v[204:207], v[64:67]
	v_mfma_f32_16x16x32_bf16 v[0:3], v[216:219], v[200:203], v[0:3]
	v_mfma_f32_16x16x32_bf16 v[0:3], v[234:237], v[204:207], v[0:3]
	s_setprio 0
	s_add_i32 s67, s67, 2
	s_add_u32 s65, s65, 0x100
	s_addc_u32 s66, s66, 0
	s_cmp_gt_u32 s67, 29
	s_mov_b64 s[8:9], s[10:11]
	s_barrier
	s_cbranch_scc0 .LBB0_840
	s_lshl_b32 s8, s0, 8
	s_lshl_b32 s1, s1, 7
	v_mov_b32_e32 v80, v225
	v_mov_b32_e32 v193, v163
	s_add_i32 s8, s8, s58
	s_or_b32 s1, s1, s53
	s_lshl_b32 s0, s0, 3
	v_add_u32_e32 v190, s8, v193
	v_lshl_add_u32 v188, v80, 3, s1
	v_ashrrev_i32_e32 v191, 31, v190
	v_ashrrev_i32_e32 v189, 31, v188
	v_lshl_add_u64 v[78:79], v[190:191], 2, s[4:5]
	v_lshlrev_b64 v[90:91], 2, v[188:189]
	global_load_dword v196, v[78:79], off
	global_load_dword v192, v[78:79], off offset:64
	global_load_dword v194, v[78:79], off offset:128
	global_load_dword v200, v[78:79], off offset:192
	global_load_dword v199, v[78:79], off offset:256
	global_load_dword v77, v[78:79], off offset:320
	global_load_dword v76, v[78:79], off offset:384
	global_load_dword v191, v[78:79], off offset:448
	v_lshl_add_u64 v[78:79], s[14:15], 0, v[90:91]
	v_lshl_add_u64 v[80:81], s[20:21], 0, v[90:91]
	global_load_dwordx4 v[102:105], v[78:79], off
	global_load_dwordx4 v[94:97], v[80:81], off
	v_lshl_add_u64 v[78:79], s[22:23], 0, v[90:91]
	global_load_dwordx4 v[98:101], v[78:79], off
	v_lshl_add_u64 v[78:79], s[16:17], 0, v[90:91]
	global_load_dwordx4 v[106:109], v[78:79], off
	v_lshl_add_u64 v[78:79], s[24:25], 0, v[90:91]
	v_lshl_add_u64 v[80:81], s[26:27], 0, v[90:91]
	v_lshl_add_u64 v[82:83], s[28:29], 0, v[90:91]
	v_lshl_add_u64 v[90:91], s[30:31], 0, v[90:91]
	global_load_dwordx4 v[86:89], v[78:79], off
	s_nop 0
	global_load_dwordx4 v[78:81], v[80:81], off
	s_add_i32 s0, s0, s59
	global_load_dwordx4 v[82:85], v[82:83], off
	v_add_u32_e32 v195, s0, v193
	global_load_dwordx4 v[90:93], v[90:91], off
	v_cmp_gt_i32_e64 s[12:13], 2, v193
	s_waitcnt vmcnt(0)
	v_fmamk_f32 v196, v196, 0x3a000000, v230
	v_rsq_f32_e32 v198, v196
	v_mad_i64_i32 v[196:197], s[0:1], v195, s62, 0
	v_lshl_add_u64 v[196:197], s[70:71], 0, v[196:197]
	v_pk_mul_f32 v[160:161], v[160:161], v[198:199] op_sel_hi:[1,0]
	v_pk_mul_f32 v[158:159], v[158:159], v[198:199] op_sel_hi:[1,0]
	v_pk_mul_f32 v[156:157], v[156:157], v[198:199] op_sel_hi:[1,0]
	v_pk_mul_f32 v[154:155], v[154:155], v[198:199] op_sel_hi:[1,0]
	v_lshl_add_u64 v[196:197], v[188:189], 2, v[196:197]
	s_and_saveexec_b64 s[0:1], s[12:13]
	s_cbranch_execz .LBB0_843
	v_add_co_u32_e32 v202, vcc, 0x5000, v196
	global_store_dwordx4 v[196:197], v[158:161], off
	s_nop 0
	v_addc_co_u32_e32 v203, vcc, 0, v197, vcc
	global_store_dwordx4 v[202:203], v[154:157], off offset:2048
